# v84: retention-item staging: 12 exec-masked loads issued together (distinct quads), LDS writes after vmcnt(11-k)
# speedup vs baseline: 1.0047x; 1.0047x over previous
.LBB0_631:
	s_andn2_b64 vcc, exec, s[0:1]
	s_cbranch_vccnz .LBB0_306
	s_mov_b64 s[6:7], s[54:55]
	s_ashr_i32 s23, s76, 4
	s_and_b32 s22, s76, 15
	s_mul_i32 s9, s23, 0x4488000
	s_mul_hi_i32 s8, s23, 0x4488000
	s_add_u32 s6, s6, s9
	s_addc_u32 s7, s7, s8
	s_add_u32 s6, s6, 0x198a0200
	s_mov_b64 s[0:1], s[54:55]
	s_waitcnt vmcnt(7)
	v_mov_b32_e32 v9, v148
	s_addc_u32 s7, s7, 0
	s_waitcnt vmcnt(6)
	v_mov_b32_e32 v10, v148
	s_cmp_lg_u32 s22, 0
	s_cselect_b64 s[8:9], -1, 0
	v_readfirstlane_b32 s26, v9
	s_lshl_b32 s27, s22, 7
	s_mov_b32 s98, s47
	s_ashr_i32 s99, s47, 31
	s_lshl_b64 s[98:99], s[98:99], 4
	s_lshl_b64 s[84:85], s[98:99], 1
	s_lshl_b32 s32, s96, 4
	v_and_b32_e32 v8, 31, v9
	v_ashrrev_i32_e32 v64, 5, v9
	v_lshlrev_b32_e32 v0, 4, v8
	v_add_u32_e32 v65, s27, v64
	v_mov_b64_e32 v[68:69], s[6:7]
	v_mad_i64_i32 v[68:69], s[30:31], v65, s47, v[68:69]
	s_lshl_b32 s14, s57, 1
	v_lshl_add_u64 v[68:69], v[68:69], 0, s[14:15]
	v_lshl_add_u64 v[68:69], v[68:69], 0, v[0:1]
	v_add_co_u32_e32 v68, vcc, 0x4000, v68
	s_nop 1
	v_addc_co_u32_e32 v69, vcc, 0, v69, vcc
	v_ashrrev_i32_e32 v76, 4, v9
	v_and_b32_e32 v82, 15, v9
	v_lshlrev_b32_e32 v82, 4, v82
	v_mov_b32_e32 v83, 0
	v_add_u32_e32 v77, s27, v76
	v_mov_b64_e32 v[80:81], s[6:7]
	v_mad_i64_i32 v[80:81], s[30:31], v77, s47, v[80:81]
	v_readlane_b32 s14, v254, 22
	s_nop 0
	s_lshl_b32 s14, s14, 1
	v_lshl_add_u64 v[80:81], v[80:81], 0, s[14:15]
	v_lshl_add_u64 v[80:81], v[80:81], 0, v[82:83]
	v_add_co_u32_e32 v80, vcc, 0x3000, v80
	s_nop 1
	v_addc_co_u32_e32 v81, vcc, 0, v81, vcc
	v_mul_lo_u32 v70, v64, s96
	v_lshl_add_u32 v70, v8, 4, v70
	v_mul_u32_u24_e32 v78, 0x140, v76
	v_add_u32_e32 v78, v78, v82
	v_add_u32_e32 v78, 0x12000, v78
	v_mov_b32_e32 v65, v64
	v_cmp_lt_i32_e32 vcc, s11, v65
	s_or_b64 s[30:31], s[8:9], vcc
	v_mov_b32_e32 v16, 0
	v_mov_b32_e32 v17, 0
	v_mov_b32_e32 v18, 0
	v_mov_b32_e32 v19, 0
	s_and_saveexec_b64 s[100:101], s[30:31]
	s_nop 0
	global_load_dwordx4 v[16:19], v[68:69], off
	s_or_b64 exec, exec, s[100:101]
	v_lshl_add_u64 v[68:69], v[68:69], 0, s[98:99]
	v_add_u32_e32 v65, 16, v64
	v_cmp_lt_i32_e32 vcc, s11, v65
	s_or_b64 s[30:31], s[8:9], vcc
	v_mov_b32_e32 v20, 0
	v_mov_b32_e32 v21, 0
	v_mov_b32_e32 v22, 0
	v_mov_b32_e32 v23, 0
	s_and_saveexec_b64 s[100:101], s[30:31]
	s_nop 0
	global_load_dwordx4 v[20:23], v[68:69], off
	s_or_b64 exec, exec, s[100:101]
	v_lshl_add_u64 v[68:69], v[68:69], 0, s[98:99]
	v_add_u32_e32 v65, 32, v64
	v_cmp_lt_i32_e32 vcc, s11, v65
	s_or_b64 s[30:31], s[8:9], vcc
	v_mov_b32_e32 v24, 0
	v_mov_b32_e32 v25, 0
	v_mov_b32_e32 v26, 0
	v_mov_b32_e32 v27, 0
	s_and_saveexec_b64 s[100:101], s[30:31]
	s_nop 0
	global_load_dwordx4 v[24:27], v[68:69], off
	s_or_b64 exec, exec, s[100:101]
	v_lshl_add_u64 v[68:69], v[68:69], 0, s[98:99]
	v_add_u32_e32 v65, 48, v64
	v_cmp_lt_i32_e32 vcc, s11, v65
	s_or_b64 s[30:31], s[8:9], vcc
	v_mov_b32_e32 v28, 0
	v_mov_b32_e32 v29, 0
	v_mov_b32_e32 v30, 0
	v_mov_b32_e32 v31, 0
	s_and_saveexec_b64 s[100:101], s[30:31]
	s_nop 0
	global_load_dwordx4 v[28:31], v[68:69], off
	s_or_b64 exec, exec, s[100:101]
	v_lshl_add_u64 v[68:69], v[68:69], 0, s[98:99]
	v_add_u32_e32 v65, 64, v64
	v_cmp_lt_i32_e32 vcc, s11, v65
	s_or_b64 s[30:31], s[8:9], vcc
	v_mov_b32_e32 v32, 0
	v_mov_b32_e32 v33, 0
	v_mov_b32_e32 v34, 0
	v_mov_b32_e32 v35, 0
	s_and_saveexec_b64 s[100:101], s[30:31]
	s_nop 0
	global_load_dwordx4 v[32:35], v[68:69], off
	s_or_b64 exec, exec, s[100:101]
	v_lshl_add_u64 v[68:69], v[68:69], 0, s[98:99]
	v_add_u32_e32 v65, 80, v64
	v_cmp_lt_i32_e32 vcc, s11, v65
	s_or_b64 s[30:31], s[8:9], vcc
	v_mov_b32_e32 v36, 0
	v_mov_b32_e32 v37, 0
	v_mov_b32_e32 v38, 0
	v_mov_b32_e32 v39, 0
	s_and_saveexec_b64 s[100:101], s[30:31]
	s_nop 0
	global_load_dwordx4 v[36:39], v[68:69], off
	s_or_b64 exec, exec, s[100:101]
	v_lshl_add_u64 v[68:69], v[68:69], 0, s[98:99]
	v_add_u32_e32 v65, 96, v64
	v_cmp_lt_i32_e32 vcc, s11, v65
	s_or_b64 s[30:31], s[8:9], vcc
	v_mov_b32_e32 v40, 0
	v_mov_b32_e32 v41, 0
	v_mov_b32_e32 v42, 0
	v_mov_b32_e32 v43, 0
	s_and_saveexec_b64 s[100:101], s[30:31]
	s_nop 0
	global_load_dwordx4 v[40:43], v[68:69], off
	s_or_b64 exec, exec, s[100:101]
	v_lshl_add_u64 v[68:69], v[68:69], 0, s[98:99]
	v_add_u32_e32 v65, 112, v64
	v_cmp_lt_i32_e32 vcc, s11, v65
	s_or_b64 s[30:31], s[8:9], vcc
	v_mov_b32_e32 v44, 0
	v_mov_b32_e32 v45, 0
	v_mov_b32_e32 v46, 0
	v_mov_b32_e32 v47, 0
	s_and_saveexec_b64 s[100:101], s[30:31]
	s_nop 0
	global_load_dwordx4 v[44:47], v[68:69], off
	s_or_b64 exec, exec, s[100:101]
	v_mov_b32_e32 v77, v76
	v_cmp_lt_i32_e32 vcc, s11, v77
	s_or_b64 s[30:31], s[8:9], vcc
	v_mov_b32_e32 v48, 0
	v_mov_b32_e32 v49, 0
	v_mov_b32_e32 v50, 0
	v_mov_b32_e32 v51, 0
	s_and_saveexec_b64 s[100:101], s[30:31]
	s_nop 0
	global_load_dwordx4 v[48:51], v[80:81], off offset:2048
	s_or_b64 exec, exec, s[100:101]
	v_lshl_add_u64 v[80:81], v[80:81], 0, s[84:85]
	v_add_u32_e32 v77, 32, v76
	v_cmp_lt_i32_e32 vcc, s11, v77
	s_or_b64 s[30:31], s[8:9], vcc
	v_mov_b32_e32 v52, 0
	v_mov_b32_e32 v53, 0
	v_mov_b32_e32 v54, 0
	v_mov_b32_e32 v55, 0
	s_and_saveexec_b64 s[100:101], s[30:31]
	s_nop 0
	global_load_dwordx4 v[52:55], v[80:81], off offset:2048
	s_or_b64 exec, exec, s[100:101]
	v_lshl_add_u64 v[80:81], v[80:81], 0, s[84:85]
	v_add_u32_e32 v77, 64, v76
	v_cmp_lt_i32_e32 vcc, s11, v77
	s_or_b64 s[30:31], s[8:9], vcc
	v_mov_b32_e32 v56, 0
	v_mov_b32_e32 v57, 0
	v_mov_b32_e32 v58, 0
	v_mov_b32_e32 v59, 0
	s_and_saveexec_b64 s[100:101], s[30:31]
	s_nop 0
	global_load_dwordx4 v[56:59], v[80:81], off offset:2048
	s_or_b64 exec, exec, s[100:101]
	v_lshl_add_u64 v[80:81], v[80:81], 0, s[84:85]
	v_add_u32_e32 v77, 96, v76
	v_cmp_lt_i32_e32 vcc, s11, v77
	s_or_b64 s[30:31], s[8:9], vcc
	v_mov_b32_e32 v60, 0
	v_mov_b32_e32 v61, 0
	v_mov_b32_e32 v62, 0
	v_mov_b32_e32 v63, 0
	s_and_saveexec_b64 s[100:101], s[30:31]
	s_nop 0
	global_load_dwordx4 v[60:63], v[80:81], off offset:2048
	s_or_b64 exec, exec, s[100:101]
	s_waitcnt vmcnt(11)
	ds_write_b128 v70, v[16:19]
	v_add_u32_e32 v70, s32, v70
	s_waitcnt vmcnt(10)
	ds_write_b128 v70, v[20:23]
	v_add_u32_e32 v70, s32, v70
	s_waitcnt vmcnt(9)
	ds_write_b128 v70, v[24:27]
	v_add_u32_e32 v70, s32, v70
	s_waitcnt vmcnt(8)
	ds_write_b128 v70, v[28:31]
	v_add_u32_e32 v70, s32, v70
	s_waitcnt vmcnt(7)
	ds_write_b128 v70, v[32:35]
	v_add_u32_e32 v70, s32, v70
	s_waitcnt vmcnt(6)
	ds_write_b128 v70, v[36:39]
	v_add_u32_e32 v70, s32, v70
	s_waitcnt vmcnt(5)
	ds_write_b128 v70, v[40:43]
	v_add_u32_e32 v70, s32, v70
	s_waitcnt vmcnt(4)
	ds_write_b128 v70, v[44:47]
	v_sub_u32_e32 v71, 0x7f, v76
	v_cvt_f32_i32_e32 v71, v71
	v_mul_f32_e32 v71, v210, v71
	v_exp_f32_e32 v74, v71
	s_waitcnt vmcnt(3)
	v_lshlrev_b32_e32 v72, 16, v48
	v_and_b32_e32 v73, 0xffff0000, v48
	v_pk_mul_f32 v[72:73], v[74:75], v[72:73] op_sel_hi:[0,1]
	v_cvt_pk_bf16_f32 v48, v72, v73
	v_lshlrev_b32_e32 v72, 16, v49
	v_and_b32_e32 v73, 0xffff0000, v49
	v_pk_mul_f32 v[72:73], v[74:75], v[72:73] op_sel_hi:[0,1]
	v_cvt_pk_bf16_f32 v49, v72, v73
	v_lshlrev_b32_e32 v72, 16, v50
	v_and_b32_e32 v73, 0xffff0000, v50
	v_pk_mul_f32 v[72:73], v[74:75], v[72:73] op_sel_hi:[0,1]
	v_cvt_pk_bf16_f32 v50, v72, v73
	v_lshlrev_b32_e32 v72, 16, v51
	v_and_b32_e32 v73, 0xffff0000, v51
	v_pk_mul_f32 v[72:73], v[74:75], v[72:73] op_sel_hi:[0,1]
	v_cvt_pk_bf16_f32 v51, v72, v73
	ds_write_b128 v78, v[48:51]
	v_add_u32_e32 v78, 0x2800, v78
	v_sub_u32_e32 v71, 95, v76
	v_cvt_f32_i32_e32 v71, v71
	v_mul_f32_e32 v71, v210, v71
	v_exp_f32_e32 v74, v71
	s_waitcnt vmcnt(2)
	v_lshlrev_b32_e32 v72, 16, v52
	v_and_b32_e32 v73, 0xffff0000, v52
	v_pk_mul_f32 v[72:73], v[74:75], v[72:73] op_sel_hi:[0,1]
	v_cvt_pk_bf16_f32 v52, v72, v73
	v_lshlrev_b32_e32 v72, 16, v53
	v_and_b32_e32 v73, 0xffff0000, v53
	v_pk_mul_f32 v[72:73], v[74:75], v[72:73] op_sel_hi:[0,1]
	v_cvt_pk_bf16_f32 v53, v72, v73
	v_lshlrev_b32_e32 v72, 16, v54
	v_and_b32_e32 v73, 0xffff0000, v54
	v_pk_mul_f32 v[72:73], v[74:75], v[72:73] op_sel_hi:[0,1]
	v_cvt_pk_bf16_f32 v54, v72, v73
	v_lshlrev_b32_e32 v72, 16, v55
	v_and_b32_e32 v73, 0xffff0000, v55
	v_pk_mul_f32 v[72:73], v[74:75], v[72:73] op_sel_hi:[0,1]
	v_cvt_pk_bf16_f32 v55, v72, v73
	ds_write_b128 v78, v[52:55]
	v_add_u32_e32 v78, 0x2800, v78
	v_sub_u32_e32 v71, 63, v76
	v_cvt_f32_i32_e32 v71, v71
	v_mul_f32_e32 v71, v210, v71
	v_exp_f32_e32 v74, v71
	s_waitcnt vmcnt(1)
	v_lshlrev_b32_e32 v72, 16, v56
	v_and_b32_e32 v73, 0xffff0000, v56
	v_pk_mul_f32 v[72:73], v[74:75], v[72:73] op_sel_hi:[0,1]
	v_cvt_pk_bf16_f32 v56, v72, v73
	v_lshlrev_b32_e32 v72, 16, v57
	v_and_b32_e32 v73, 0xffff0000, v57
	v_pk_mul_f32 v[72:73], v[74:75], v[72:73] op_sel_hi:[0,1]
	v_cvt_pk_bf16_f32 v57, v72, v73
	v_lshlrev_b32_e32 v72, 16, v58
	v_and_b32_e32 v73, 0xffff0000, v58
	v_pk_mul_f32 v[72:73], v[74:75], v[72:73] op_sel_hi:[0,1]
	v_cvt_pk_bf16_f32 v58, v72, v73
	v_lshlrev_b32_e32 v72, 16, v59
	v_and_b32_e32 v73, 0xffff0000, v59
	v_pk_mul_f32 v[72:73], v[74:75], v[72:73] op_sel_hi:[0,1]
	v_cvt_pk_bf16_f32 v59, v72, v73
	ds_write_b128 v78, v[56:59]
	v_add_u32_e32 v78, 0x2800, v78
	v_sub_u32_e32 v71, 31, v76
	v_cvt_f32_i32_e32 v71, v71
	v_mul_f32_e32 v71, v210, v71
	v_exp_f32_e32 v74, v71
	s_waitcnt vmcnt(0)
	v_lshlrev_b32_e32 v72, 16, v60
	v_and_b32_e32 v73, 0xffff0000, v60
	v_pk_mul_f32 v[72:73], v[74:75], v[72:73] op_sel_hi:[0,1]
	v_cvt_pk_bf16_f32 v60, v72, v73
	v_lshlrev_b32_e32 v72, 16, v61
	v_and_b32_e32 v73, 0xffff0000, v61
	v_pk_mul_f32 v[72:73], v[74:75], v[72:73] op_sel_hi:[0,1]
	v_cvt_pk_bf16_f32 v61, v72, v73
	v_lshlrev_b32_e32 v72, 16, v62
	v_and_b32_e32 v73, 0xffff0000, v62
	v_pk_mul_f32 v[72:73], v[74:75], v[72:73] op_sel_hi:[0,1]
	v_cvt_pk_bf16_f32 v62, v72, v73
	v_lshlrev_b32_e32 v72, 16, v63
	v_and_b32_e32 v73, 0xffff0000, v63
	v_pk_mul_f32 v[72:73], v[74:75], v[72:73] op_sel_hi:[0,1]
	v_cvt_pk_bf16_f32 v63, v72, v73
	ds_write_b128 v78, v[60:63]
	v_bfe_u32 v66, v9, 5, 1
	s_ashr_i32 s7, s26, 6
	v_bfe_u32 v2, v9, 2, 2
	v_lshlrev_b32_e32 v5, 2, v9
	v_and_b32_e32 v3, 16, v9
	v_lshl_or_b32 v2, v66, 3, v2
	s_lshl_b32 s6, s7, 5
	v_and_b32_e32 v5, 12, v5
	v_mul_u32_u24_e32 v4, 0x240, v2
	v_or3_b32 v6, v3, s6, v5
	s_cmp_lg_u32 0, -1
	v_lshl_add_u32 v67, v6, 1, v4
	s_cselect_b32 s8, 0, 0
	s_waitcnt lgkmcnt(0)
	s_barrier
	v_add_u32_e32 v4, s8, v67
	v_mul_u32_u24_e32 v2, 0x140, v2
	v_or_b32_e32 v3, v5, v3
	ds_read_b64_tr_b16 v[18:19], v4 offset:0
	v_lshl_or_b32 v88, v3, 1, v2
	s_add_i32 s9, s8, 0x12000
	ds_read_b64_tr_b16 v[20:21], v4 offset:0x900
	v_add_u32_e32 v14, s9, v88
	ds_read_b64_tr_b16 v[2:3], v14 offset:0
	ds_read_b64_tr_b16 v[4:5], v14 offset:0x500
	ds_read_b64_tr_b16 v[6:7], v14 offset:64
	v_and_b32_e32 v0, 31, v9
	ds_read_b64_tr_b16 v[8:9], v14 offset:0x540
	ds_read_b64_tr_b16 v[10:11], v14 offset:0x80
	ds_read_b64_tr_b16 v[12:13], v14 offset:0x580
	ds_read_b64_tr_b16 v[22:23], v14 offset:0xc0
	ds_read_b64_tr_b16 v[24:25], v14 offset:0x5c0
	s_waitcnt lgkmcnt(0)
	s_add_i32 s9, s8, 0x2400
	v_add_u32_e32 v72, s9, v67
	ds_read_b64_tr_b16 v[68:69], v72 offset:0
	s_add_i32 s9, s8, 0x13400
	ds_read_b64_tr_b16 v[70:71], v72 offset:0x900
	v_add_u32_e32 v89, s9, v88
	ds_read_b64_tr_b16 v[72:73], v89 offset:0
	ds_read_b64_tr_b16 v[74:75], v89 offset:0x500
	ds_read_b64_tr_b16 v[76:77], v89 offset:64
	ds_read_b64_tr_b16 v[78:79], v89 offset:0x540
	ds_read_b64_tr_b16 v[80:81], v89 offset:0x80
	ds_read_b64_tr_b16 v[82:83], v89 offset:0x580
	ds_read_b64_tr_b16 v[84:85], v89 offset:0xc0
	ds_read_b64_tr_b16 v[86:87], v89 offset:0x5c0
	s_waitcnt lgkmcnt(0)
	v_mfma_f32_32x32x16_bf16 v[34:49], v[18:21], v[2:5], 0
	v_mfma_f32_32x32x16_bf16 v[50:65], v[18:21], v[6:9], 0
	v_mfma_f32_32x32x16_bf16 v[2:17], v[18:21], v[10:13], 0
	v_mfma_f32_32x32x16_bf16 v[18:33], v[18:21], v[22:25], 0
	s_add_i32 s9, s8, 0x4800
	v_mfma_f32_32x32x16_bf16 v[34:49], v[68:71], v[72:75], v[34:49]
	v_add_u32_e32 v72, s9, v67
	s_add_i32 s9, s8, 0x14800
	v_add_u32_e32 v89, s9, v88
	v_mfma_f32_32x32x16_bf16 v[50:65], v[68:71], v[76:79], v[50:65]
	v_mfma_f32_32x32x16_bf16 v[2:17], v[68:71], v[80:83], v[2:17]
	v_mfma_f32_32x32x16_bf16 v[18:33], v[68:71], v[84:87], v[18:33]
	ds_read_b64_tr_b16 v[68:69], v72 offset:0
	ds_read_b64_tr_b16 v[70:71], v72 offset:0x900
	ds_read_b64_tr_b16 v[72:73], v89 offset:0
	ds_read_b64_tr_b16 v[74:75], v89 offset:0x500
	ds_read_b64_tr_b16 v[76:77], v89 offset:64
	ds_read_b64_tr_b16 v[78:79], v89 offset:0x540
	ds_read_b64_tr_b16 v[80:81], v89 offset:0x80
	ds_read_b64_tr_b16 v[82:83], v89 offset:0x580
	ds_read_b64_tr_b16 v[84:85], v89 offset:0xc0
	ds_read_b64_tr_b16 v[86:87], v89 offset:0x5c0
	s_waitcnt lgkmcnt(0)
	s_add_i32 s9, s8, 0x6c00
	v_mfma_f32_32x32x16_bf16 v[34:49], v[68:71], v[72:75], v[34:49]
	v_add_u32_e32 v72, s9, v67
	s_add_i32 s9, s8, 0x15c00
	v_add_u32_e32 v89, s9, v88
	v_mfma_f32_32x32x16_bf16 v[50:65], v[68:71], v[76:79], v[50:65]
	v_mfma_f32_32x32x16_bf16 v[2:17], v[68:71], v[80:83], v[2:17]
	v_mfma_f32_32x32x16_bf16 v[18:33], v[68:71], v[84:87], v[18:33]
	ds_read_b64_tr_b16 v[68:69], v72 offset:0
	ds_read_b64_tr_b16 v[70:71], v72 offset:0x900
	ds_read_b64_tr_b16 v[72:73], v89 offset:0
	ds_read_b64_tr_b16 v[74:75], v89 offset:0x500
	ds_read_b64_tr_b16 v[76:77], v89 offset:64
	ds_read_b64_tr_b16 v[78:79], v89 offset:0x540
	ds_read_b64_tr_b16 v[80:81], v89 offset:0x80
	ds_read_b64_tr_b16 v[82:83], v89 offset:0x580
	ds_read_b64_tr_b16 v[84:85], v89 offset:0xc0
	ds_read_b64_tr_b16 v[86:87], v89 offset:0x5c0
	s_waitcnt lgkmcnt(0)
	s_add_i32 s9, s8, 0x9000
	v_mfma_f32_32x32x16_bf16 v[34:49], v[68:71], v[72:75], v[34:49]
	v_add_u32_e32 v72, s9, v67
	s_add_i32 s9, s8, 0x17000
	v_add_u32_e32 v89, s9, v88
	v_mfma_f32_32x32x16_bf16 v[50:65], v[68:71], v[76:79], v[50:65]
	v_mfma_f32_32x32x16_bf16 v[2:17], v[68:71], v[80:83], v[2:17]
	v_mfma_f32_32x32x16_bf16 v[18:33], v[68:71], v[84:87], v[18:33]
	ds_read_b64_tr_b16 v[68:69], v72 offset:0
	ds_read_b64_tr_b16 v[70:71], v72 offset:0x900
	ds_read_b64_tr_b16 v[72:73], v89 offset:0
	ds_read_b64_tr_b16 v[74:75], v89 offset:0x500
	ds_read_b64_tr_b16 v[76:77], v89 offset:64
	ds_read_b64_tr_b16 v[78:79], v89 offset:0x540
	ds_read_b64_tr_b16 v[80:81], v89 offset:0x80
	ds_read_b64_tr_b16 v[82:83], v89 offset:0x580
	ds_read_b64_tr_b16 v[84:85], v89 offset:0xc0
	ds_read_b64_tr_b16 v[86:87], v89 offset:0x5c0
	s_waitcnt lgkmcnt(0)
	s_add_i32 s9, s8, 0xb400
	v_mfma_f32_32x32x16_bf16 v[34:49], v[68:71], v[72:75], v[34:49]
	v_add_u32_e32 v72, s9, v67
	s_add_i32 s9, s8, 0x18400
	v_add_u32_e32 v89, s9, v88
	v_mfma_f32_32x32x16_bf16 v[50:65], v[68:71], v[76:79], v[50:65]
	v_mfma_f32_32x32x16_bf16 v[2:17], v[68:71], v[80:83], v[2:17]
	v_mfma_f32_32x32x16_bf16 v[18:33], v[68:71], v[84:87], v[18:33]
	ds_read_b64_tr_b16 v[68:69], v72 offset:0
	ds_read_b64_tr_b16 v[70:71], v72 offset:0x900
	ds_read_b64_tr_b16 v[72:73], v89 offset:0
	ds_read_b64_tr_b16 v[74:75], v89 offset:0x500
	ds_read_b64_tr_b16 v[76:77], v89 offset:64
	ds_read_b64_tr_b16 v[78:79], v89 offset:0x540
	ds_read_b64_tr_b16 v[80:81], v89 offset:0x80
	ds_read_b64_tr_b16 v[82:83], v89 offset:0x580
	ds_read_b64_tr_b16 v[84:85], v89 offset:0xc0
	ds_read_b64_tr_b16 v[86:87], v89 offset:0x5c0
	s_waitcnt lgkmcnt(0)
	s_add_i32 s9, s8, 0xd800
	v_mfma_f32_32x32x16_bf16 v[34:49], v[68:71], v[72:75], v[34:49]
	v_add_u32_e32 v72, s9, v67
	s_add_i32 s9, s8, 0x19800
	v_add_u32_e32 v89, s9, v88
	v_mfma_f32_32x32x16_bf16 v[50:65], v[68:71], v[76:79], v[50:65]
	v_mfma_f32_32x32x16_bf16 v[2:17], v[68:71], v[80:83], v[2:17]
	v_mfma_f32_32x32x16_bf16 v[18:33], v[68:71], v[84:87], v[18:33]
	ds_read_b64_tr_b16 v[68:69], v72 offset:0
	ds_read_b64_tr_b16 v[70:71], v72 offset:0x900
	ds_read_b64_tr_b16 v[72:73], v89 offset:0
	ds_read_b64_tr_b16 v[74:75], v89 offset:0x500
	ds_read_b64_tr_b16 v[76:77], v89 offset:64
	ds_read_b64_tr_b16 v[78:79], v89 offset:0x540
	ds_read_b64_tr_b16 v[80:81], v89 offset:0x80
	ds_read_b64_tr_b16 v[82:83], v89 offset:0x580
	ds_read_b64_tr_b16 v[84:85], v89 offset:0xc0
	ds_read_b64_tr_b16 v[86:87], v89 offset:0x5c0
	s_waitcnt lgkmcnt(0)
	s_add_i32 s9, s8, 0xfc00
	v_mfma_f32_32x32x16_bf16 v[34:49], v[68:71], v[72:75], v[34:49]
	v_add_u32_e32 v67, s9, v67
	s_add_i32 s8, s8, 0x1ac00
	v_add_u32_e32 v88, s8, v88
	v_mfma_f32_32x32x16_bf16 v[50:65], v[68:71], v[76:79], v[50:65]
	v_mfma_f32_32x32x16_bf16 v[2:17], v[68:71], v[80:83], v[2:17]
	v_mfma_f32_32x32x16_bf16 v[18:33], v[68:71], v[84:87], v[18:33]
	ds_read_b64_tr_b16 v[68:69], v67 offset:0
	ds_read_b64_tr_b16 v[70:71], v67 offset:0x900
	ds_read_b64_tr_b16 v[72:73], v88 offset:0
	ds_read_b64_tr_b16 v[74:75], v88 offset:0x500
	ds_read_b64_tr_b16 v[76:77], v88 offset:64
	ds_read_b64_tr_b16 v[78:79], v88 offset:0x540
	ds_read_b64_tr_b16 v[80:81], v88 offset:0x80
	ds_read_b64_tr_b16 v[82:83], v88 offset:0x580
	ds_read_b64_tr_b16 v[84:85], v88 offset:0xc0
	ds_read_b64_tr_b16 v[86:87], v88 offset:0x5c0
	s_waitcnt lgkmcnt(0)
	s_nop 0
	v_mfma_f32_32x32x16_bf16 v[34:49], v[68:71], v[72:75], v[34:49]
	s_lshl_b32 s7, s7, 14
	s_add_i32 s12, s7, 0
	s_lshl_b32 s7, s23, 7
	v_readlane_b32 s8, v254, 15
	s_or_b32 s7, s7, s8
	s_or_b32 s8, s7, s22
	s_ashr_i32 s9, s8, 31
	v_mfma_f32_32x32x16_bf16 v[50:65], v[68:71], v[76:79], v[50:65]
	s_lshl_b64 s[8:9], s[8:9], 17
	v_lshlrev_b32_e32 v67, 11, v66
	v_lshlrev_b32_e32 v72, 2, v0
	s_add_u32 s8, s0, s8
	v_add3_u32 v67, s12, v67, v72
	s_addc_u32 s9, s1, s9
	s_ashr_i32 s7, s6, 31
	v_mfma_f32_32x32x16_bf16 v[2:17], v[68:71], v[80:83], v[2:17]
	s_barrier
	s_nop 2
	ds_write2_b32 v67, v34, v50 offset1:32
	ds_write2_b32 v67, v35, v51 offset0:128 offset1:160
	v_add_u32_e32 v34, 0x400, v67
	s_lshl_b64 s[0:1], s[6:7], 9
	ds_write2_b32 v34, v36, v52 offset1:32
	ds_write2_b32 v34, v37, v53 offset0:128 offset1:160
	v_mfma_f32_32x32x16_bf16 v[18:33], v[68:71], v[84:87], v[18:33]
	v_add_u32_e32 v35, 0x1000, v67
	v_add_u32_e32 v36, 0x1400, v67
	s_add_u32 s0, s8, s0
	ds_write2_b32 v35, v38, v54 offset1:32
	ds_write2_b32 v35, v39, v55 offset0:128 offset1:160
	ds_write2_b32 v36, v40, v56 offset1:32
	ds_write2_b32 v36, v41, v57 offset0:128 offset1:160
	v_add_u32_e32 v37, 0x2000, v67
	v_add_u32_e32 v38, 0x2400, v67
	v_add_u32_e32 v39, 0x3000, v67
	v_add_u32_e32 v40, 0x3400, v67
	s_addc_u32 s1, s9, s1
	v_lshlrev_b32_e32 v0, 4, v0
	ds_write2_b32 v37, v42, v58 offset1:32
	ds_write2_b32 v37, v43, v59 offset0:128 offset1:160
	ds_write2_b32 v38, v44, v60 offset1:32
	ds_write2_b32 v38, v45, v61 offset0:128 offset1:160
	ds_write2_b32 v39, v46, v62 offset1:32
	ds_write2_b32 v39, v47, v63 offset0:128 offset1:160
	ds_write2_b32 v40, v48, v64 offset1:32
	ds_write2_b32 v40, v49, v65 offset0:128 offset1:160
	ds_write2_b32 v67, v2, v18 offset0:64 offset1:96
	ds_write2_b32 v67, v3, v19 offset0:192 offset1:224
	ds_write2_b32 v34, v4, v20 offset0:64 offset1:96
	ds_write2_b32 v34, v5, v21 offset0:192 offset1:224
	ds_write2_b32 v35, v6, v22 offset0:64 offset1:96
	ds_write2_b32 v35, v7, v23 offset0:192 offset1:224
	ds_write2_b32 v36, v8, v24 offset0:64 offset1:96
	ds_write2_b32 v36, v9, v25 offset0:192 offset1:224
	ds_write2_b32 v37, v10, v26 offset0:64 offset1:96
	ds_write2_b32 v37, v11, v27 offset0:192 offset1:224
	ds_write2_b32 v38, v12, v28 offset0:64 offset1:96
	ds_write2_b32 v38, v13, v29 offset0:192 offset1:224
	ds_write2_b32 v39, v14, v30 offset0:64 offset1:96
	ds_write2_b32 v39, v15, v31 offset0:192 offset1:224
	ds_write2_b32 v40, v16, v32 offset0:64 offset1:96
	ds_write2_b32 v40, v17, v33 offset0:192 offset1:224
	v_lshlrev_b32_e32 v6, 9, v66
	v_lshl_add_u64 v[8:9], s[0:1], 0, v[0:1]
	s_mov_b64 s[0:1], 0x354c0200
	s_waitcnt lgkmcnt(0)
	v_add3_u32 v14, s12, v0, v6
	v_lshl_add_u64 v[8:9], v[8:9], 0, s[0:1]
	v_mov_b32_e32 v7, v1
	ds_read_b128 v[2:5], v14
	v_lshl_add_u64 v[10:11], v[8:9], 0, v[6:7]
	s_waitcnt lgkmcnt(0)
	s_nop 1
	global_store_dwordx4 v[10:11], v[2:5], off sc1
	s_nop 1
	s_mov_b64 s[0:1], 0x400
	ds_read_b128 v[2:5], v14 offset:1024
	v_lshl_add_u64 v[12:13], v[10:11], 0, s[0:1]
	s_waitcnt lgkmcnt(0)
	s_nop 1
	global_store_dwordx4 v[12:13], v[2:5], off sc1
	s_nop 1
	s_mov_b64 s[0:1], 0x800
	ds_read_b128 v[2:5], v14 offset:2048
	v_lshl_add_u64 v[12:13], v[10:11], 0, s[0:1]
	s_waitcnt lgkmcnt(0)
	s_nop 1
	global_store_dwordx4 v[12:13], v[2:5], off sc1
	s_nop 1
	s_mov_b64 s[0:1], 0xc00
	ds_read_b128 v[2:5], v14 offset:3072
	v_lshl_add_u64 v[10:11], v[10:11], 0, s[0:1]
	s_waitcnt lgkmcnt(0)
	s_nop 1
	global_store_dwordx4 v[10:11], v[2:5], off sc1
	s_nop 1
	v_or_b32_e32 v0, 0x1000, v6
	ds_read_b128 v[2:5], v14 offset:4096
	v_lshl_add_u64 v[10:11], v[8:9], 0, v[0:1]
	s_waitcnt lgkmcnt(0)
	s_nop 1
	global_store_dwordx4 v[10:11], v[2:5], off sc1
	s_nop 1
	v_or_b32_e32 v0, 0x1400, v6
	ds_read_b128 v[2:5], v14 offset:5120
	v_lshl_add_u64 v[10:11], v[8:9], 0, v[0:1]
	s_waitcnt lgkmcnt(0)
	s_nop 1
	global_store_dwordx4 v[10:11], v[2:5], off sc1
	s_nop 1
	v_or_b32_e32 v0, 0x1800, v6
	ds_read_b128 v[2:5], v14 offset:6144
	v_lshl_add_u64 v[10:11], v[8:9], 0, v[0:1]
	s_waitcnt lgkmcnt(0)
	s_nop 1
	global_store_dwordx4 v[10:11], v[2:5], off sc1
	s_nop 1
	v_or_b32_e32 v0, 0x1c00, v6
	ds_read_b128 v[2:5], v14 offset:7168
	v_lshl_add_u64 v[10:11], v[8:9], 0, v[0:1]
	s_waitcnt lgkmcnt(0)
	s_nop 1
	global_store_dwordx4 v[10:11], v[2:5], off sc1
	s_nop 1
	v_or_b32_e32 v0, 0x2000, v6
	ds_read_b128 v[2:5], v14 offset:8192
	v_lshl_add_u64 v[10:11], v[8:9], 0, v[0:1]
	s_waitcnt lgkmcnt(0)
	s_nop 1
	global_store_dwordx4 v[10:11], v[2:5], off sc1
	s_nop 1
	v_or_b32_e32 v0, 0x2400, v6
	ds_read_b128 v[2:5], v14 offset:9216
	v_lshl_add_u64 v[10:11], v[8:9], 0, v[0:1]
	s_waitcnt lgkmcnt(0)
	s_nop 1
	global_store_dwordx4 v[10:11], v[2:5], off sc1
	s_nop 1
	v_or_b32_e32 v0, 0x2800, v6
	ds_read_b128 v[2:5], v14 offset:10240
	v_lshl_add_u64 v[10:11], v[8:9], 0, v[0:1]
	s_waitcnt lgkmcnt(0)
	s_nop 1
	global_store_dwordx4 v[10:11], v[2:5], off sc1
	s_nop 1
	v_or_b32_e32 v0, 0x2c00, v6
	ds_read_b128 v[2:5], v14 offset:11264
	v_lshl_add_u64 v[10:11], v[8:9], 0, v[0:1]
	s_waitcnt lgkmcnt(0)
	s_nop 1
	global_store_dwordx4 v[10:11], v[2:5], off sc1
	s_nop 1
	v_or_b32_e32 v0, 0x3000, v6
	ds_read_b128 v[2:5], v14 offset:12288
	v_lshl_add_u64 v[10:11], v[8:9], 0, v[0:1]
	s_waitcnt lgkmcnt(0)
	s_nop 1
	global_store_dwordx4 v[10:11], v[2:5], off sc1
	s_nop 1
	v_or_b32_e32 v0, 0x3400, v6
	ds_read_b128 v[2:5], v14 offset:13312
	v_lshl_add_u64 v[10:11], v[8:9], 0, v[0:1]
	s_waitcnt lgkmcnt(0)
	s_nop 1
	global_store_dwordx4 v[10:11], v[2:5], off sc1
	s_nop 1
	v_or_b32_e32 v0, 0x3800, v6
	ds_read_b128 v[2:5], v14 offset:14336
	v_lshl_add_u64 v[10:11], v[8:9], 0, v[0:1]
	s_waitcnt lgkmcnt(0)
	s_nop 1
	global_store_dwordx4 v[10:11], v[2:5], off sc1
	s_nop 1
	v_or_b32_e32 v0, 0x3c00, v6
	ds_read_b128 v[2:5], v14 offset:15360
	v_lshl_add_u64 v[6:7], v[8:9], 0, v[0:1]
	s_waitcnt lgkmcnt(0)
	s_nop 1
	global_store_dwordx4 v[6:7], v[2:5], off sc1
	s_nop 1
	s_barrier
	s_waitcnt vmcnt(0)
	s_barrier
	s_mov_b64 s[0:1], exec
	v_readlane_b32 s6, v253, 0
	v_readlane_b32 s7, v253, 1
	s_and_b64 s[6:7], s[0:1], s[6:7]
	s_xor_b64 s[0:1], s[6:7], s[0:1]
	s_mov_b64 exec, s[6:7]
	s_cbranch_execz .LBB0_305
	s_mov_b64 s[6:7], exec
	v_mbcnt_lo_u32_b32 v0, s6, 0
	v_mbcnt_hi_u32_b32 v0, s7, v0
	v_cmp_eq_u32_e32 vcc, 0, v0
	s_and_saveexec_b64 s[8:9], vcc
	s_xor_b64 s[8:9], exec, s[8:9]
	s_cbranch_execz .LBB0_304
	s_ashr_i32 s12, s76, 1
	s_and_b32 s12, s12, -8
	v_readlane_b32 s13, v254, 52
	s_or_b32 s12, s12, s13
	s_ashr_i32 s13, s12, 31
	s_lshl_b64 s[12:13], s[12:13], 2
	v_readlane_b32 s14, v255, 18
	s_add_u32 s12, s14, s12
	v_readlane_b32 s14, v255, 19
	s_addc_u32 s13, s14, s13
	s_bcnt1_i32_b64 s6, s[6:7]
	v_mov_b32_e32 v0, s6
	global_atomic_add v1, v0, s[12:13]
	s_branch .LBB0_304
